# v12 combo: batched residual+xbuf loads, no drain at unit start, hoisted rope table loads in mix-in epilogue, SwiGLU output in LDS-image order
# speedup vs baseline: 1.0060x; 1.0060x over previous
; __device__ __forceinline__ unsigned cvtpk(float lo, float hi) { f32x2 v = {lo, hi}; bf16x2_t b = __builtin_convertvector(v, bf16x2_t); return __builtin_bit_cast(unsigned, b); }
;     __device__ __forceinline__ void operator()(const f32x4 (&acc)[2][2][4][2], const Unit& u, int wr, int wc, int fr, int fq) const {
;     ...
;                 if (gp) { float ss = 0.f;
; #pragma unroll
;                     for (int n = 0; n < 2; ++n)
; #pragma unroll
;                         for (int e = 0; e < 4; ++e) ss += a[n][e] * a[n][e] + bb[n][e] * bb[n][e];
;                     ss += __shfl_xor(ss, 16); ss += __shfl_xor(ss, 32);
;                     r = rsqrtf(ss * (1.0f / 64) + EPS) * scale; }
; #pragma unroll
;                 for (int n = 0; n < 2; ++n) { a[n] = a[n] * r * ga[n]; bb[n] = bb[n] * r * gb[n]; }
;                 const size_t o = ((size_t)(b * Hn + h) * SEQ + s_) * 64 + 8 * fq;
;                 if (two) { u32x4 w; w.x = cvtpk(a[0][0], a[0][1]); w.y = cvtpk(a[0][2], a[0][3]); w.z = cvtpk(a[1][0], a[1][1]); w.w = cvtpk(a[1][2], a[1][3]); *(u32x4*)(QC + o) = w;
;                     w.x = cvtpk(bb[0][0], bb[0][1]); w.y = cvtpk(bb[0][2], bb[0][3]); w.z = cvtpk(bb[1][0], bb[1][1]); w.w = cvtpk(bb[1][2], bb[1][3]); *(u32x4*)(QC + o + 32) = w; }
;                 if (rope) {
; #pragma unroll
;                     for (int n = 0; n < 2; ++n) { const f32x4 cs = *(const f32x4*)(C64 + (size_t)row * 32 + 8 * fq + 4 * n), sn = *(const f32x4*)(S64 + (size_t)row * 32 + 8 * fq + 4 * n);
;                         const f32x4 ya = a[n], yb = bb[n]; a[n] = ya * cs - yb * sn; bb[n] = yb * cs + ya * sn; } }
;                 u32x4 w; w.x = cvtpk(a[0][0], a[0][1]); w.y = cvtpk(a[0][2], a[0][3]); w.z = cvtpk(a[1][0], a[1][1]); w.w = cvtpk(a[1][2], a[1][3]); *(u32x4*)(dst + o) = w;
;                 w.x = cvtpk(bb[0][0], bb[0][1]); w.y = cvtpk(bb[0][2], bb[0][3]); w.z = cvtpk(bb[1][0], bb[1][1]); w.w = cvtpk(bb[1][2], bb[1][3]); *(u32x4*)(dst + o + 32) = w;
.LBB0_93:
	v_readlane_b32 s36, v254, 33
	v_cvt_pk_bf16_f32 v176, v176, v177
	v_cvt_pk_bf16_f32 v177, v178, v179
	v_cvt_pk_bf16_f32 v178, v180, v181
	v_cvt_pk_bf16_f32 v179, v182, v183
	v_lshl_add_u64 v[174:175], v[174:175], 1, s[72:73]
	v_cvt_pk_bf16_f32 v166, v166, v167
	v_cvt_pk_bf16_f32 v167, v168, v169
	v_cvt_pk_bf16_f32 v168, v170, v171
	v_cvt_pk_bf16_f32 v169, v172, v173
	s_and_b64 vcc, exec, s[14:15]
	v_mov_b32_e32 v170, s29
	v_add_u32_e32 v242, 0x10, v164
	v_ashrrev_i32_e32 v243, 31, v242
	v_lshlrev_b64 v[242:243], 7, v[242:243]
	v_lshl_add_u64 v[244:245], v[156:157], 0, v[242:243]
	v_lshl_add_u64 v[242:243], v[158:159], 0, v[242:243]
	global_load_dwordx4 v[226:229], v[244:245], off
	global_load_dwordx4 v[230:233], v[242:243], off
	global_load_dwordx4 v[234:237], v[244:245], off offset:16
	global_load_dwordx4 v[238:241], v[242:243], off offset:16
	flat_store_dwordx4 v[174:175], v[176:179]
	flat_store_dwordx4 v[174:175], v[166:169] offset:64
	s_cbranch_vccnz .LBB0_95
	s_nop 0
	v_pk_mul_f32 v[168:169], v[94:95], v[94:95]
	v_pk_mul_f32 v[166:167], v[96:97], v[96:97]
	v_pk_fma_f32 v[168:169], v[118:119], v[118:119], v[168:169]
	v_pk_fma_f32 v[166:167], v[120:121], v[120:121], v[166:167]
	v_add_f32_e32 v165, v168, v169
	v_pk_mul_f32 v[172:173], v[90:91], v[90:91]
	v_add_f32_e32 v165, v166, v165
	v_pk_fma_f32 v[172:173], v[114:115], v[114:115], v[172:173]
	v_add_f32_e32 v165, v167, v165
	v_and_b32_e32 v167, 64, v209
	v_pk_mul_f32 v[170:171], v[92:93], v[92:93]
	v_add_f32_e32 v165, v172, v165
	v_xor_b32_e32 v166, 16, v209
	v_add_u32_e32 v167, 64, v167
	v_pk_fma_f32 v[170:171], v[116:117], v[116:117], v[170:171]
	v_add_f32_e32 v165, v173, v165
	v_cmp_lt_i32_e32 vcc, v166, v167
	v_add_f32_e32 v165, v170, v165
	v_add_f32_e32 v165, v171, v165
	v_cndmask_b32_e32 v166, v209, v166, vcc
	v_lshlrev_b32_e32 v166, 2, v166
	ds_bpermute_b32 v166, v166, v165
	s_mov_b32 s2, 0x800000
	s_waitcnt lgkmcnt(0)
	v_add_f32_e32 v165, v165, v166
	v_xor_b32_e32 v166, 32, v209
	v_cmp_lt_i32_e32 vcc, v166, v167
	s_nop 1
	v_cndmask_b32_e32 v166, v209, v166, vcc
	v_lshlrev_b32_e32 v166, 2, v166
	ds_bpermute_b32 v166, v166, v165
	s_waitcnt lgkmcnt(0)
	v_add_f32_e32 v165, v165, v166
	v_fmamk_f32 v165, v165, 0x3c800000, v201
	v_mul_f32_e32 v166, 0x4b800000, v165
	v_cmp_gt_f32_e32 vcc, s2, v165
	s_nop 1
	v_cndmask_b32_e32 v165, v165, v166, vcc
	v_rsq_f32_e32 v165, v165
	s_nop 0
	v_mul_f32_e32 v166, 0x45800000, v165
	v_cndmask_b32_e32 v165, v165, v166, vcc
	v_mul_f32_e32 v170, s29, v165

; __device__ __forceinline__ unsigned cvtpk(float lo, float hi) { f32x2 v = {lo, hi}; bf16x2_t b = __builtin_convertvector(v, bf16x2_t); return __builtin_bit_cast(unsigned, b); }
;     __device__ __forceinline__ void operator()(const f32x4 (&acc)[2][2][4][2], const Unit& u, int wr, int wc, int fr, int fq) const {
;     ...
;                 if (gp) { float ss = 0.f;
; #pragma unroll
;                     for (int n = 0; n < 2; ++n)
; #pragma unroll
;                         for (int e = 0; e < 4; ++e) ss += a[n][e] * a[n][e] + bb[n][e] * bb[n][e];
;                     ss += __shfl_xor(ss, 16); ss += __shfl_xor(ss, 32);
;                     r = rsqrtf(ss * (1.0f / 64) + EPS) * scale; }
; #pragma unroll
;                 for (int n = 0; n < 2; ++n) { a[n] = a[n] * r * ga[n]; bb[n] = bb[n] * r * gb[n]; }
;                 const size_t o = ((size_t)(b * Hn + h) * SEQ + s_) * 64 + 8 * fq;
;                 if (two) { u32x4 w; w.x = cvtpk(a[0][0], a[0][1]); w.y = cvtpk(a[0][2], a[0][3]); w.z = cvtpk(a[1][0], a[1][1]); w.w = cvtpk(a[1][2], a[1][3]); *(u32x4*)(QC + o) = w;
;                     w.x = cvtpk(bb[0][0], bb[0][1]); w.y = cvtpk(bb[0][2], bb[0][3]); w.z = cvtpk(bb[1][0], bb[1][1]); w.w = cvtpk(bb[1][2], bb[1][3]); *(u32x4*)(QC + o + 32) = w; }
;                 if (rope) {
; #pragma unroll
;                     for (int n = 0; n < 2; ++n) { const f32x4 cs = *(const f32x4*)(C64 + (size_t)row * 32 + 8 * fq + 4 * n), sn = *(const f32x4*)(S64 + (size_t)row * 32 + 8 * fq + 4 * n);
;                         const f32x4 ya = a[n], yb = bb[n]; a[n] = ya * cs - yb * sn; bb[n] = yb * cs + ya * sn; } }
;                 u32x4 w; w.x = cvtpk(a[0][0], a[0][1]); w.y = cvtpk(a[0][2], a[0][3]); w.z = cvtpk(a[1][0], a[1][1]); w.w = cvtpk(a[1][2], a[1][3]); *(u32x4*)(dst + o) = w;
;                 w.x = cvtpk(bb[0][0], bb[0][1]); w.y = cvtpk(bb[0][2], bb[0][3]); w.z = cvtpk(bb[1][0], bb[1][1]); w.w = cvtpk(bb[1][2], bb[1][3]); *(u32x4*)(dst + o + 32) = w;
.LBB0_97:
	s_and_b64 vcc, exec, s[18:19]
	s_cbranch_vccnz .LBB0_99
	v_ashrrev_i32_e32 v185, 31, v184
	v_lshlrev_b64 v[184:185], 7, v[184:185]
	v_lshl_add_u64 v[198:199], v[156:157], 0, v[184:185]
	v_lshl_add_u64 v[184:185], v[158:159], 0, v[184:185]
	s_waitcnt vmcnt(2) lgkmcnt(0)
	v_pk_mul_f32 v[184:185], v[166:167], v[232:233]
	v_pk_mul_f32 v[198:199], v[168:169], v[230:231]
	v_pk_mul_f32 v[202:203], v[170:171], v[240:241]
	v_pk_mul_f32 v[204:205], v[172:173], v[238:239]
	v_pk_fma_f32 v[184:185], v[178:179], v[228:229], v[184:185] neg_lo:[0,0,1] neg_hi:[0,0,1]
	v_pk_fma_f32 v[198:199], v[176:177], v[226:227], v[198:199] neg_lo:[0,0,1] neg_hi:[0,0,1]
	v_pk_fma_f32 v[202:203], v[180:181], v[236:237], v[202:203] neg_lo:[0,0,1] neg_hi:[0,0,1]
	v_pk_fma_f32 v[204:205], v[182:183], v[234:235], v[204:205] neg_lo:[0,0,1] neg_hi:[0,0,1]
	v_pk_mul_f32 v[178:179], v[178:179], v[232:233]
	v_pk_mul_f32 v[176:177], v[176:177], v[230:231]
	v_pk_mul_f32 v[180:181], v[180:181], v[240:241]
	v_pk_mul_f32 v[182:183], v[182:183], v[238:239]
	v_pk_fma_f32 v[166:167], v[166:167], v[228:229], v[178:179]
	v_pk_fma_f32 v[168:169], v[168:169], v[226:227], v[176:177]
	v_pk_fma_f32 v[170:171], v[170:171], v[236:237], v[180:181]
	v_pk_fma_f32 v[172:173], v[172:173], v[234:235], v[182:183]
	v_mov_b32_e32 v176, v198
	v_mov_b32_e32 v177, v199
	v_mov_b32_e32 v178, v184
	v_mov_b32_e32 v179, v185
	v_mov_b32_e32 v182, v204
	v_mov_b32_e32 v183, v205
	v_mov_b32_e32 v180, v202
	v_mov_b32_e32 v181, v203
.LBB0_99:
	v_cvt_pk_bf16_f32 v176, v176, v177
	v_cvt_pk_bf16_f32 v177, v178, v179
	v_cvt_pk_bf16_f32 v178, v182, v183
	v_cvt_pk_bf16_f32 v179, v180, v181
	v_lshl_add_u64 v[180:181], v[174:175], 1, s[72:73]
	v_add_u32_e32 v242, 0x20, v164
	v_ashrrev_i32_e32 v243, 31, v242
	v_lshlrev_b64 v[242:243], 7, v[242:243]
	v_lshl_add_u64 v[244:245], v[156:157], 0, v[242:243]
	v_lshl_add_u64 v[242:243], v[158:159], 0, v[242:243]
	global_load_dwordx4 v[226:229], v[244:245], off
	global_load_dwordx4 v[230:233], v[242:243], off
	global_load_dwordx4 v[234:237], v[244:245], off offset:16
	global_load_dwordx4 v[238:241], v[242:243], off offset:16
	flat_store_dwordx4 v[180:181], v[176:179]
	v_cvt_pk_bf16_f32 v174, v168, v169
	v_cvt_pk_bf16_f32 v175, v166, v167
	v_cvt_pk_bf16_f32 v176, v172, v173
	v_cvt_pk_bf16_f32 v177, v170, v171
	s_and_b64 vcc, exec, s[14:15]
	v_mov_b32_e32 v170, s29
	flat_store_dwordx4 v[180:181], v[174:177] offset:64
	s_cbranch_vccnz .LBB0_101
	v_pk_mul_f32 v[168:169], v[78:79], v[78:79]
	v_pk_mul_f32 v[166:167], v[80:81], v[80:81]
	v_pk_fma_f32 v[168:169], v[102:103], v[102:103], v[168:169]
	v_pk_fma_f32 v[166:167], v[104:105], v[104:105], v[166:167]
	v_add_f32_e32 v165, v168, v169
	v_pk_mul_f32 v[172:173], v[74:75], v[74:75]
	v_add_f32_e32 v165, v166, v165
	v_pk_fma_f32 v[172:173], v[98:99], v[98:99], v[172:173]
	v_add_f32_e32 v165, v167, v165
	v_and_b32_e32 v167, 64, v209
	v_pk_mul_f32 v[170:171], v[76:77], v[76:77]
	v_add_f32_e32 v165, v172, v165
	v_xor_b32_e32 v166, 16, v209
	v_add_u32_e32 v167, 64, v167
	v_pk_fma_f32 v[170:171], v[100:101], v[100:101], v[170:171]
	v_add_f32_e32 v165, v173, v165
	v_cmp_lt_i32_e32 vcc, v166, v167
	v_add_f32_e32 v165, v170, v165
	v_add_f32_e32 v165, v171, v165
	v_cndmask_b32_e32 v166, v209, v166, vcc
	v_lshlrev_b32_e32 v166, 2, v166
	ds_bpermute_b32 v166, v166, v165
	s_mov_b32 s2, 0x800000
	s_waitcnt lgkmcnt(0)
	v_add_f32_e32 v165, v165, v166
	v_xor_b32_e32 v166, 32, v209
	v_cmp_lt_i32_e32 vcc, v166, v167
	s_nop 1
	v_cndmask_b32_e32 v166, v209, v166, vcc
	v_lshlrev_b32_e32 v166, 2, v166
	ds_bpermute_b32 v166, v166, v165
	s_waitcnt lgkmcnt(0)
	v_add_f32_e32 v165, v165, v166
	v_fmamk_f32 v165, v165, 0x3c800000, v201
	v_mul_f32_e32 v166, 0x4b800000, v165
	v_cmp_gt_f32_e32 vcc, s2, v165
	s_nop 1
	v_cndmask_b32_e32 v165, v165, v166, vcc
	v_rsq_f32_e32 v165, v165
	s_nop 0
	v_mul_f32_e32 v166, 0x45800000, v165
	v_cndmask_b32_e32 v165, v165, v166, vcc
	v_mul_f32_e32 v170, s29, v165

; __device__ __forceinline__ unsigned cvtpk(float lo, float hi) { f32x2 v = {lo, hi}; bf16x2_t b = __builtin_convertvector(v, bf16x2_t); return __builtin_bit_cast(unsigned, b); }
;     __device__ __forceinline__ void operator()(const f32x4 (&acc)[2][2][4][2], const Unit& u, int wr, int wc, int fr, int fq) const {
;     ...
;                 if (gp) { float ss = 0.f;
; #pragma unroll
;                     for (int n = 0; n < 2; ++n)
; #pragma unroll
;                         for (int e = 0; e < 4; ++e) ss += a[n][e] * a[n][e] + bb[n][e] * bb[n][e];
;                     ss += __shfl_xor(ss, 16); ss += __shfl_xor(ss, 32);
;                     r = rsqrtf(ss * (1.0f / 64) + EPS) * scale; }
; #pragma unroll
;                 for (int n = 0; n < 2; ++n) { a[n] = a[n] * r * ga[n]; bb[n] = bb[n] * r * gb[n]; }
;                 const size_t o = ((size_t)(b * Hn + h) * SEQ + s_) * 64 + 8 * fq;
;                 if (two) { u32x4 w; w.x = cvtpk(a[0][0], a[0][1]); w.y = cvtpk(a[0][2], a[0][3]); w.z = cvtpk(a[1][0], a[1][1]); w.w = cvtpk(a[1][2], a[1][3]); *(u32x4*)(QC + o) = w;
;                     w.x = cvtpk(bb[0][0], bb[0][1]); w.y = cvtpk(bb[0][2], bb[0][3]); w.z = cvtpk(bb[1][0], bb[1][1]); w.w = cvtpk(bb[1][2], bb[1][3]); *(u32x4*)(QC + o + 32) = w; }
;                 if (rope) {
; #pragma unroll
;                     for (int n = 0; n < 2; ++n) { const f32x4 cs = *(const f32x4*)(C64 + (size_t)row * 32 + 8 * fq + 4 * n), sn = *(const f32x4*)(S64 + (size_t)row * 32 + 8 * fq + 4 * n);
;                         const f32x4 ya = a[n], yb = bb[n]; a[n] = ya * cs - yb * sn; bb[n] = yb * cs + ya * sn; } }
;                 u32x4 w; w.x = cvtpk(a[0][0], a[0][1]); w.y = cvtpk(a[0][2], a[0][3]); w.z = cvtpk(a[1][0], a[1][1]); w.w = cvtpk(a[1][2], a[1][3]); *(u32x4*)(dst + o) = w;
;                 w.x = cvtpk(bb[0][0], bb[0][1]); w.y = cvtpk(bb[0][2], bb[0][3]); w.z = cvtpk(bb[1][0], bb[1][1]); w.w = cvtpk(bb[1][2], bb[1][3]); *(u32x4*)(dst + o + 32) = w;
.LBB0_105:
	v_cvt_pk_bf16_f32 v176, v176, v177
	v_cvt_pk_bf16_f32 v177, v178, v179
	v_cvt_pk_bf16_f32 v178, v182, v183
	v_cvt_pk_bf16_f32 v179, v180, v181
	v_lshl_add_u64 v[180:181], v[174:175], 1, s[72:73]
	v_add_u32_e32 v242, 0x30, v164
	v_ashrrev_i32_e32 v243, 31, v242
	v_lshlrev_b64 v[242:243], 7, v[242:243]
	v_lshl_add_u64 v[244:245], v[156:157], 0, v[242:243]
	v_lshl_add_u64 v[242:243], v[158:159], 0, v[242:243]
	global_load_dwordx4 v[226:229], v[244:245], off
	global_load_dwordx4 v[230:233], v[242:243], off
	global_load_dwordx4 v[234:237], v[244:245], off offset:16
	global_load_dwordx4 v[238:241], v[242:243], off offset:16
	flat_store_dwordx4 v[180:181], v[176:179]
	v_cvt_pk_bf16_f32 v174, v168, v169
	v_cvt_pk_bf16_f32 v175, v166, v167
	v_cvt_pk_bf16_f32 v176, v172, v173
	v_cvt_pk_bf16_f32 v177, v170, v171
	s_and_b64 vcc, exec, s[14:15]
	v_mov_b32_e32 v170, s29
	flat_store_dwordx4 v[180:181], v[174:177] offset:64
	s_cbranch_vccnz .LBB0_107
	v_pk_mul_f32 v[168:169], v[70:71], v[70:71]
	v_pk_mul_f32 v[166:167], v[72:73], v[72:73]
	v_pk_fma_f32 v[168:169], v[86:87], v[86:87], v[168:169]
	v_pk_fma_f32 v[166:167], v[88:89], v[88:89], v[166:167]
	v_add_f32_e32 v165, v168, v169
	v_pk_mul_f32 v[172:173], v[66:67], v[66:67]
	v_add_f32_e32 v165, v166, v165
	v_pk_fma_f32 v[172:173], v[82:83], v[82:83], v[172:173]
	v_add_f32_e32 v165, v167, v165
	v_and_b32_e32 v167, 64, v209
	v_pk_mul_f32 v[170:171], v[68:69], v[68:69]
	v_add_f32_e32 v165, v172, v165
	v_xor_b32_e32 v166, 16, v209
	v_add_u32_e32 v167, 64, v167
	v_pk_fma_f32 v[170:171], v[84:85], v[84:85], v[170:171]
	v_add_f32_e32 v165, v173, v165
	v_cmp_lt_i32_e32 vcc, v166, v167
	v_add_f32_e32 v165, v170, v165
	v_add_f32_e32 v165, v171, v165
	v_cndmask_b32_e32 v166, v209, v166, vcc
	v_lshlrev_b32_e32 v166, 2, v166
	ds_bpermute_b32 v166, v166, v165
	s_mov_b32 s2, 0x800000
	s_waitcnt lgkmcnt(0)
	v_add_f32_e32 v165, v165, v166
	v_xor_b32_e32 v166, 32, v209
	v_cmp_lt_i32_e32 vcc, v166, v167
	s_nop 1
	v_cndmask_b32_e32 v166, v209, v166, vcc
	v_lshlrev_b32_e32 v166, 2, v166
	ds_bpermute_b32 v166, v166, v165
	s_waitcnt lgkmcnt(0)
	v_add_f32_e32 v165, v165, v166
	v_fmamk_f32 v165, v165, 0x3c800000, v201
	v_mul_f32_e32 v166, 0x4b800000, v165
	v_cmp_gt_f32_e32 vcc, s2, v165
	s_nop 1
	v_cndmask_b32_e32 v165, v165, v166, vcc
	v_rsq_f32_e32 v165, v165
	s_nop 0
	v_mul_f32_e32 v166, 0x45800000, v165
	v_cndmask_b32_e32 v165, v165, v166, vcc
	v_mul_f32_e32 v170, s29, v165

; __device__ __forceinline__ unsigned cvtpk(float lo, float hi) { f32x2 v = {lo, hi}; bf16x2_t b = __builtin_convertvector(v, bf16x2_t); return __builtin_bit_cast(unsigned, b); }
;     __device__ __forceinline__ void operator()(const f32x4 (&acc)[2][2][4][2], const Unit& u, int wr, int wc, int fr, int fq) const {
;     ...
;                 if (gp) { float ss = 0.f;
; #pragma unroll
;                     for (int n = 0; n < 2; ++n)
; #pragma unroll
;                         for (int e = 0; e < 4; ++e) ss += a[n][e] * a[n][e] + bb[n][e] * bb[n][e];
;                     ss += __shfl_xor(ss, 16); ss += __shfl_xor(ss, 32);
;                     r = rsqrtf(ss * (1.0f / 64) + EPS) * scale; }
; #pragma unroll
;                 for (int n = 0; n < 2; ++n) { a[n] = a[n] * r * ga[n]; bb[n] = bb[n] * r * gb[n]; }
;                 const size_t o = ((size_t)(b * Hn + h) * SEQ + s_) * 64 + 8 * fq;
;                 if (two) { u32x4 w; w.x = cvtpk(a[0][0], a[0][1]); w.y = cvtpk(a[0][2], a[0][3]); w.z = cvtpk(a[1][0], a[1][1]); w.w = cvtpk(a[1][2], a[1][3]); *(u32x4*)(QC + o) = w;
;                     w.x = cvtpk(bb[0][0], bb[0][1]); w.y = cvtpk(bb[0][2], bb[0][3]); w.z = cvtpk(bb[1][0], bb[1][1]); w.w = cvtpk(bb[1][2], bb[1][3]); *(u32x4*)(QC + o + 32) = w; }
;                 if (rope) {
; #pragma unroll
;                     for (int n = 0; n < 2; ++n) { const f32x4 cs = *(const f32x4*)(C64 + (size_t)row * 32 + 8 * fq + 4 * n), sn = *(const f32x4*)(S64 + (size_t)row * 32 + 8 * fq + 4 * n);
;                         const f32x4 ya = a[n], yb = bb[n]; a[n] = ya * cs - yb * sn; bb[n] = yb * cs + ya * sn; } }
;                 u32x4 w; w.x = cvtpk(a[0][0], a[0][1]); w.y = cvtpk(a[0][2], a[0][3]); w.z = cvtpk(a[1][0], a[1][1]); w.w = cvtpk(a[1][2], a[1][3]); *(u32x4*)(dst + o) = w;
;                 w.x = cvtpk(bb[0][0], bb[0][1]); w.y = cvtpk(bb[0][2], bb[0][3]); w.z = cvtpk(bb[1][0], bb[1][1]); w.w = cvtpk(bb[1][2], bb[1][3]); *(u32x4*)(dst + o + 32) = w;
.LBB0_111:
	v_cvt_pk_bf16_f32 v176, v176, v177
	v_cvt_pk_bf16_f32 v177, v178, v179
	v_cvt_pk_bf16_f32 v178, v182, v183
	v_cvt_pk_bf16_f32 v179, v180, v181
	v_lshl_add_u64 v[180:181], v[174:175], 1, s[72:73]
	v_add_u32_e32 v242, 0x80, v164
	v_ashrrev_i32_e32 v243, 31, v242
	v_lshlrev_b64 v[242:243], 7, v[242:243]
	v_lshl_add_u64 v[244:245], v[156:157], 0, v[242:243]
	v_lshl_add_u64 v[242:243], v[158:159], 0, v[242:243]
	global_load_dwordx4 v[226:229], v[244:245], off
	global_load_dwordx4 v[230:233], v[242:243], off
	global_load_dwordx4 v[234:237], v[244:245], off offset:16
	global_load_dwordx4 v[238:241], v[242:243], off offset:16
	flat_store_dwordx4 v[180:181], v[176:179]
	v_cvt_pk_bf16_f32 v174, v168, v169
	v_cvt_pk_bf16_f32 v175, v166, v167
	v_cvt_pk_bf16_f32 v176, v172, v173
	v_cvt_pk_bf16_f32 v177, v170, v171
	s_and_b64 vcc, exec, s[14:15]
	v_mov_b32_e32 v170, s29
	flat_store_dwordx4 v[180:181], v[174:177] offset:64
	s_cbranch_vccnz .LBB0_113
	v_pk_mul_f32 v[168:169], v[46:47], v[46:47]
	v_pk_mul_f32 v[166:167], v[48:49], v[48:49]
	v_pk_fma_f32 v[168:169], v[62:63], v[62:63], v[168:169]
	v_pk_fma_f32 v[166:167], v[64:65], v[64:65], v[166:167]
	v_add_f32_e32 v165, v168, v169
	v_pk_mul_f32 v[172:173], v[42:43], v[42:43]
	v_add_f32_e32 v165, v166, v165
	v_pk_fma_f32 v[172:173], v[58:59], v[58:59], v[172:173]
	v_add_f32_e32 v165, v167, v165
	v_and_b32_e32 v167, 64, v209
	v_pk_mul_f32 v[170:171], v[44:45], v[44:45]
	v_add_f32_e32 v165, v172, v165
	v_xor_b32_e32 v166, 16, v209
	v_add_u32_e32 v167, 64, v167
	v_pk_fma_f32 v[170:171], v[60:61], v[60:61], v[170:171]
	v_add_f32_e32 v165, v173, v165
	v_cmp_lt_i32_e32 vcc, v166, v167
	v_add_f32_e32 v165, v170, v165
	v_add_f32_e32 v165, v171, v165
	v_cndmask_b32_e32 v166, v209, v166, vcc
	v_lshlrev_b32_e32 v166, 2, v166
	ds_bpermute_b32 v166, v166, v165
	s_mov_b32 s2, 0x800000
	s_waitcnt lgkmcnt(0)
	v_add_f32_e32 v165, v165, v166
	v_xor_b32_e32 v166, 32, v209
	v_cmp_lt_i32_e32 vcc, v166, v167
	s_nop 1
	v_cndmask_b32_e32 v166, v209, v166, vcc
	v_lshlrev_b32_e32 v166, 2, v166
	ds_bpermute_b32 v166, v166, v165
	s_waitcnt lgkmcnt(0)
	v_add_f32_e32 v165, v165, v166
	v_fmamk_f32 v165, v165, 0x3c800000, v201
	v_mul_f32_e32 v166, 0x4b800000, v165
	v_cmp_gt_f32_e32 vcc, s2, v165
	s_nop 1
	v_cndmask_b32_e32 v165, v165, v166, vcc
	v_rsq_f32_e32 v165, v165
	s_nop 0
	v_mul_f32_e32 v166, 0x45800000, v165
	v_cndmask_b32_e32 v165, v165, v166, vcc
	v_mul_f32_e32 v170, s29, v165

; __device__ __forceinline__ unsigned cvtpk(float lo, float hi) { f32x2 v = {lo, hi}; bf16x2_t b = __builtin_convertvector(v, bf16x2_t); return __builtin_bit_cast(unsigned, b); }
;     __device__ __forceinline__ void operator()(const f32x4 (&acc)[2][2][4][2], const Unit& u, int wr, int wc, int fr, int fq) const {
;     ...
;                 if (gp) { float ss = 0.f;
; #pragma unroll
;                     for (int n = 0; n < 2; ++n)
; #pragma unroll
;                         for (int e = 0; e < 4; ++e) ss += a[n][e] * a[n][e] + bb[n][e] * bb[n][e];
;                     ss += __shfl_xor(ss, 16); ss += __shfl_xor(ss, 32);
;                     r = rsqrtf(ss * (1.0f / 64) + EPS) * scale; }
; #pragma unroll
;                 for (int n = 0; n < 2; ++n) { a[n] = a[n] * r * ga[n]; bb[n] = bb[n] * r * gb[n]; }
;                 const size_t o = ((size_t)(b * Hn + h) * SEQ + s_) * 64 + 8 * fq;
;                 if (two) { u32x4 w; w.x = cvtpk(a[0][0], a[0][1]); w.y = cvtpk(a[0][2], a[0][3]); w.z = cvtpk(a[1][0], a[1][1]); w.w = cvtpk(a[1][2], a[1][3]); *(u32x4*)(QC + o) = w;
;                     w.x = cvtpk(bb[0][0], bb[0][1]); w.y = cvtpk(bb[0][2], bb[0][3]); w.z = cvtpk(bb[1][0], bb[1][1]); w.w = cvtpk(bb[1][2], bb[1][3]); *(u32x4*)(QC + o + 32) = w; }
;                 if (rope) {
; #pragma unroll
;                     for (int n = 0; n < 2; ++n) { const f32x4 cs = *(const f32x4*)(C64 + (size_t)row * 32 + 8 * fq + 4 * n), sn = *(const f32x4*)(S64 + (size_t)row * 32 + 8 * fq + 4 * n);
;                         const f32x4 ya = a[n], yb = bb[n]; a[n] = ya * cs - yb * sn; bb[n] = yb * cs + ya * sn; } }
;                 u32x4 w; w.x = cvtpk(a[0][0], a[0][1]); w.y = cvtpk(a[0][2], a[0][3]); w.z = cvtpk(a[1][0], a[1][1]); w.w = cvtpk(a[1][2], a[1][3]); *(u32x4*)(dst + o) = w;
;                 w.x = cvtpk(bb[0][0], bb[0][1]); w.y = cvtpk(bb[0][2], bb[0][3]); w.z = cvtpk(bb[1][0], bb[1][1]); w.w = cvtpk(bb[1][2], bb[1][3]); *(u32x4*)(dst + o + 32) = w;
.LBB0_117:
	v_cvt_pk_bf16_f32 v176, v176, v177
	v_cvt_pk_bf16_f32 v177, v178, v179
	v_cvt_pk_bf16_f32 v178, v182, v183
	v_cvt_pk_bf16_f32 v179, v180, v181
	v_lshl_add_u64 v[180:181], v[174:175], 1, s[72:73]
	v_add_u32_e32 v242, 0x90, v164
	v_ashrrev_i32_e32 v243, 31, v242
	v_lshlrev_b64 v[242:243], 7, v[242:243]
	v_lshl_add_u64 v[244:245], v[156:157], 0, v[242:243]
	v_lshl_add_u64 v[242:243], v[158:159], 0, v[242:243]
	global_load_dwordx4 v[226:229], v[244:245], off
	global_load_dwordx4 v[230:233], v[242:243], off
	global_load_dwordx4 v[234:237], v[244:245], off offset:16
	global_load_dwordx4 v[238:241], v[242:243], off offset:16
	flat_store_dwordx4 v[180:181], v[176:179]
	v_cvt_pk_bf16_f32 v174, v168, v169
	v_cvt_pk_bf16_f32 v175, v166, v167
	v_cvt_pk_bf16_f32 v176, v172, v173
	v_cvt_pk_bf16_f32 v177, v170, v171
	s_and_b64 vcc, exec, s[14:15]
	v_mov_b32_e32 v170, s29
	flat_store_dwordx4 v[180:181], v[174:177] offset:64
	s_cbranch_vccnz .LBB0_119
	v_pk_mul_f32 v[168:169], v[30:31], v[30:31]
	v_pk_mul_f32 v[166:167], v[32:33], v[32:33]
	v_pk_fma_f32 v[168:169], v[54:55], v[54:55], v[168:169]
	v_pk_fma_f32 v[166:167], v[56:57], v[56:57], v[166:167]
	v_add_f32_e32 v165, v168, v169
	v_pk_mul_f32 v[172:173], v[26:27], v[26:27]
	v_add_f32_e32 v165, v166, v165
	v_pk_fma_f32 v[172:173], v[50:51], v[50:51], v[172:173]
	v_add_f32_e32 v165, v167, v165
	v_and_b32_e32 v167, 64, v209
	v_pk_mul_f32 v[170:171], v[28:29], v[28:29]
	v_add_f32_e32 v165, v172, v165
	v_xor_b32_e32 v166, 16, v209
	v_add_u32_e32 v167, 64, v167
	v_pk_fma_f32 v[170:171], v[52:53], v[52:53], v[170:171]
	v_add_f32_e32 v165, v173, v165
	v_cmp_lt_i32_e32 vcc, v166, v167
	v_add_f32_e32 v165, v170, v165
	v_add_f32_e32 v165, v171, v165
	v_cndmask_b32_e32 v166, v209, v166, vcc
	v_lshlrev_b32_e32 v166, 2, v166
	ds_bpermute_b32 v166, v166, v165
	s_mov_b32 s2, 0x800000
	s_waitcnt lgkmcnt(0)
	v_add_f32_e32 v165, v165, v166
	v_xor_b32_e32 v166, 32, v209
	v_cmp_lt_i32_e32 vcc, v166, v167
	s_nop 1
	v_cndmask_b32_e32 v166, v209, v166, vcc
	v_lshlrev_b32_e32 v166, 2, v166
	ds_bpermute_b32 v166, v166, v165
	s_waitcnt lgkmcnt(0)
	v_add_f32_e32 v165, v165, v166
	v_fmamk_f32 v165, v165, 0x3c800000, v201
	v_mul_f32_e32 v166, 0x4b800000, v165
	v_cmp_gt_f32_e32 vcc, s2, v165
	s_nop 1
	v_cndmask_b32_e32 v165, v165, v166, vcc
	v_rsq_f32_e32 v165, v165
	s_nop 0
	v_mul_f32_e32 v166, 0x45800000, v165
	v_cndmask_b32_e32 v165, v165, v166, vcc
	v_mul_f32_e32 v170, s29, v165

; __device__ __forceinline__ unsigned cvtpk(float lo, float hi) { f32x2 v = {lo, hi}; bf16x2_t b = __builtin_convertvector(v, bf16x2_t); return __builtin_bit_cast(unsigned, b); }
;     __device__ __forceinline__ void operator()(const f32x4 (&acc)[2][2][4][2], const Unit& u, int wr, int wc, int fr, int fq) const {
;     ...
;                 if (gp) { float ss = 0.f;
; #pragma unroll
;                     for (int n = 0; n < 2; ++n)
; #pragma unroll
;                         for (int e = 0; e < 4; ++e) ss += a[n][e] * a[n][e] + bb[n][e] * bb[n][e];
;                     ss += __shfl_xor(ss, 16); ss += __shfl_xor(ss, 32);
;                     r = rsqrtf(ss * (1.0f / 64) + EPS) * scale; }
; #pragma unroll
;                 for (int n = 0; n < 2; ++n) { a[n] = a[n] * r * ga[n]; bb[n] = bb[n] * r * gb[n]; }
;                 const size_t o = ((size_t)(b * Hn + h) * SEQ + s_) * 64 + 8 * fq;
;                 if (two) { u32x4 w; w.x = cvtpk(a[0][0], a[0][1]); w.y = cvtpk(a[0][2], a[0][3]); w.z = cvtpk(a[1][0], a[1][1]); w.w = cvtpk(a[1][2], a[1][3]); *(u32x4*)(QC + o) = w;
;                     w.x = cvtpk(bb[0][0], bb[0][1]); w.y = cvtpk(bb[0][2], bb[0][3]); w.z = cvtpk(bb[1][0], bb[1][1]); w.w = cvtpk(bb[1][2], bb[1][3]); *(u32x4*)(QC + o + 32) = w; }
;                 if (rope) {
; #pragma unroll
;                     for (int n = 0; n < 2; ++n) { const f32x4 cs = *(const f32x4*)(C64 + (size_t)row * 32 + 8 * fq + 4 * n), sn = *(const f32x4*)(S64 + (size_t)row * 32 + 8 * fq + 4 * n);
;                         const f32x4 ya = a[n], yb = bb[n]; a[n] = ya * cs - yb * sn; bb[n] = yb * cs + ya * sn; } }
;                 u32x4 w; w.x = cvtpk(a[0][0], a[0][1]); w.y = cvtpk(a[0][2], a[0][3]); w.z = cvtpk(a[1][0], a[1][1]); w.w = cvtpk(a[1][2], a[1][3]); *(u32x4*)(dst + o) = w;
;                 w.x = cvtpk(bb[0][0], bb[0][1]); w.y = cvtpk(bb[0][2], bb[0][3]); w.z = cvtpk(bb[1][0], bb[1][1]); w.w = cvtpk(bb[1][2], bb[1][3]); *(u32x4*)(dst + o + 32) = w;
.LBB0_123:
	v_cvt_pk_bf16_f32 v176, v176, v177
	v_cvt_pk_bf16_f32 v177, v178, v179
	v_cvt_pk_bf16_f32 v178, v182, v183
	v_cvt_pk_bf16_f32 v179, v180, v181
	v_lshl_add_u64 v[180:181], v[174:175], 1, s[72:73]
	v_add_u32_e32 v242, 0xa0, v164
	v_ashrrev_i32_e32 v243, 31, v242
	v_lshlrev_b64 v[242:243], 7, v[242:243]
	v_lshl_add_u64 v[244:245], v[156:157], 0, v[242:243]
	v_lshl_add_u64 v[242:243], v[158:159], 0, v[242:243]
	global_load_dwordx4 v[226:229], v[244:245], off
	global_load_dwordx4 v[230:233], v[242:243], off
	global_load_dwordx4 v[234:237], v[244:245], off offset:16
	global_load_dwordx4 v[238:241], v[242:243], off offset:16
	flat_store_dwordx4 v[180:181], v[176:179]
	v_cvt_pk_bf16_f32 v174, v168, v169
	v_cvt_pk_bf16_f32 v175, v166, v167
	v_cvt_pk_bf16_f32 v176, v172, v173
	v_cvt_pk_bf16_f32 v177, v170, v171
	s_and_b64 vcc, exec, s[14:15]
	v_mov_b32_e32 v170, s29
	flat_store_dwordx4 v[180:181], v[174:177] offset:64
	s_cbranch_vccnz .LBB0_125
	v_pk_mul_f32 v[168:169], v[12:13], v[12:13]
	v_pk_mul_f32 v[166:167], v[14:15], v[14:15]
	v_pk_fma_f32 v[168:169], v[38:39], v[38:39], v[168:169]
	v_pk_fma_f32 v[166:167], v[40:41], v[40:41], v[166:167]
	v_add_f32_e32 v165, v168, v169
	v_pk_mul_f32 v[172:173], v[8:9], v[8:9]
	v_add_f32_e32 v165, v166, v165
	v_pk_fma_f32 v[172:173], v[34:35], v[34:35], v[172:173]
	v_add_f32_e32 v165, v167, v165
	v_and_b32_e32 v167, 64, v209
	v_pk_mul_f32 v[170:171], v[10:11], v[10:11]
	v_add_f32_e32 v165, v172, v165
	v_xor_b32_e32 v166, 16, v209
	v_add_u32_e32 v167, 64, v167
	v_pk_fma_f32 v[170:171], v[36:37], v[36:37], v[170:171]
	v_add_f32_e32 v165, v173, v165
	v_cmp_lt_i32_e32 vcc, v166, v167
	v_add_f32_e32 v165, v170, v165
	v_add_f32_e32 v165, v171, v165
	v_cndmask_b32_e32 v166, v209, v166, vcc
	v_lshlrev_b32_e32 v166, 2, v166
	ds_bpermute_b32 v166, v166, v165
	s_mov_b32 s2, 0x800000
	s_waitcnt lgkmcnt(0)
	v_add_f32_e32 v165, v165, v166
	v_xor_b32_e32 v166, 32, v209
	v_cmp_lt_i32_e32 vcc, v166, v167
	s_nop 1
	v_cndmask_b32_e32 v166, v209, v166, vcc
	v_lshlrev_b32_e32 v166, 2, v166
	ds_bpermute_b32 v166, v166, v165
	s_waitcnt lgkmcnt(0)
	v_add_f32_e32 v165, v165, v166
	v_fmamk_f32 v165, v165, 0x3c800000, v201
	v_mul_f32_e32 v166, 0x4b800000, v165
	v_cmp_gt_f32_e32 vcc, s2, v165
	s_nop 1
	v_cndmask_b32_e32 v165, v165, v166, vcc
	v_rsq_f32_e32 v165, v165
	s_nop 0
	v_mul_f32_e32 v166, 0x45800000, v165
	v_cndmask_b32_e32 v165, v165, v166, vcc
	v_mul_f32_e32 v170, s29, v165

; template <class Epi>
; __device__ __forceinline__ void gemm_phase(LAS unsigned char* lds, const Gemm g, const StaticOrder& S, const Epi& E) {
;     ...
; #pragma unroll
;         for (int a = 0; a < 2; ++a)
; #pragma unroll
;             for (int b = 0; b < 2; ++b)
; #pragma unroll
;                 for (int m = 0; m < 4; ++m)
; #pragma unroll
;                     for (int n = 0; n < 2; ++n) acc[a][b][m][n] = (f32x4){0.f, 0.f, 0.f, 0.f};
;         cur = nxt; cA = nA; cB = nB; ++ui;
.LBB0_650:
	s_add_u32 s35, s38, 0x100
	s_addc_u32 s37, s39, 0
	s_add_u32 s38, s40, s100
	v_mov_b32_e32 v70, 0
	s_addc_u32 s39, s41, 0
	s_mov_b32 s40, 0
	v_mov_b32_e32 v71, v70
	v_mov_b32_e32 v72, v70
	v_mov_b32_e32 v73, v70
	v_mov_b32_e32 v82, v70
	v_mov_b32_e32 v83, v70
	v_mov_b32_e32 v84, v70
	v_mov_b32_e32 v85, v70
	v_mov_b32_e32 v118, v70
	v_mov_b32_e32 v119, v70
	v_mov_b32_e32 v120, v70
	v_mov_b32_e32 v121, v70
	v_mov_b32_e32 v114, v70
	v_mov_b32_e32 v115, v70
	v_mov_b32_e32 v116, v70
	v_mov_b32_e32 v117, v70
	v_mov_b32_e32 v90, v70
	v_mov_b32_e32 v91, v70
	v_mov_b32_e32 v92, v70
	v_mov_b32_e32 v93, v70
	v_mov_b32_e32 v86, v70
	v_mov_b32_e32 v87, v70
	v_mov_b32_e32 v88, v70
	v_mov_b32_e32 v89, v70
	v_mov_b32_e32 v62, v70
	v_mov_b32_e32 v63, v70
	v_mov_b32_e32 v64, v70
	v_mov_b32_e32 v65, v70
	v_mov_b32_e32 v58, v70
	v_mov_b32_e32 v59, v70
	v_mov_b32_e32 v60, v70
	v_mov_b32_e32 v61, v70
	v_mov_b32_e32 v110, v70
	v_mov_b32_e32 v111, v70
	v_mov_b32_e32 v112, v70
	v_mov_b32_e32 v113, v70
	v_mov_b32_e32 v126, v70
	v_mov_b32_e32 v127, v70
	v_mov_b32_e32 v128, v70
	v_mov_b32_e32 v129, v70
	v_mov_b32_e32 v122, v70
	v_mov_b32_e32 v123, v70
	v_mov_b32_e32 v124, v70
	v_mov_b32_e32 v125, v70
	v_mov_b32_e32 v106, v70
	v_mov_b32_e32 v107, v70
	v_mov_b32_e32 v108, v70
	v_mov_b32_e32 v109, v70
	v_mov_b32_e32 v94, v70
	v_mov_b32_e32 v95, v70
	v_mov_b32_e32 v96, v70
	v_mov_b32_e32 v97, v70
	v_mov_b32_e32 v74, v70
	v_mov_b32_e32 v75, v70
	v_mov_b32_e32 v76, v70
	v_mov_b32_e32 v77, v70
	v_mov_b32_e32 v66, v70
	v_mov_b32_e32 v67, v70
	v_mov_b32_e32 v68, v70
	v_mov_b32_e32 v69, v70
	v_mov_b32_e32 v54, v70
	v_mov_b32_e32 v55, v70
	v_mov_b32_e32 v56, v70
	v_mov_b32_e32 v57, v70
	v_mov_b32_e32 v42, v70
	v_mov_b32_e32 v43, v70
	v_mov_b32_e32 v44, v70
	v_mov_b32_e32 v45, v70
	v_mov_b32_e32 v38, v70
	v_mov_b32_e32 v39, v70
	v_mov_b32_e32 v40, v70
	v_mov_b32_e32 v41, v70
	v_mov_b32_e32 v12, v70
	v_mov_b32_e32 v13, v70
	v_mov_b32_e32 v14, v70
	v_mov_b32_e32 v15, v70
	v_mov_b32_e32 v4, v70
	v_mov_b32_e32 v5, v70
	v_mov_b32_e32 v6, v70
	v_mov_b32_e32 v7, v70
	v_mov_b32_e32 v8, v70
	v_mov_b32_e32 v9, v70
	v_mov_b32_e32 v10, v70
	v_mov_b32_e32 v11, v70
	v_mov_b32_e32 v22, v70
	v_mov_b32_e32 v23, v70
	v_mov_b32_e32 v24, v70
	v_mov_b32_e32 v25, v70
	v_mov_b32_e32 v102, v70
	v_mov_b32_e32 v103, v70
	v_mov_b32_e32 v104, v70
	v_mov_b32_e32 v105, v70
	v_mov_b32_e32 v98, v70
	v_mov_b32_e32 v99, v70
	v_mov_b32_e32 v100, v70
	v_mov_b32_e32 v101, v70
	v_mov_b32_e32 v46, v70
	v_mov_b32_e32 v47, v70
	v_mov_b32_e32 v48, v70
	v_mov_b32_e32 v49, v70
	v_mov_b32_e32 v30, v70
	v_mov_b32_e32 v31, v70
	v_mov_b32_e32 v32, v70
	v_mov_b32_e32 v33, v70
	v_mov_b32_e32 v18, v70
	v_mov_b32_e32 v19, v70
	v_mov_b32_e32 v20, v70
	v_mov_b32_e32 v21, v70
	v_mov_b32_e32 v0, v70
	v_mov_b32_e32 v1, v70
	v_mov_b32_e32 v2, v70
	v_mov_b32_e32 v3, v70
	v_mov_b32_e32 v34, v70
	v_mov_b32_e32 v35, v70
	v_mov_b32_e32 v36, v70
	v_mov_b32_e32 v37, v70
	v_mov_b32_e32 v26, v70
	v_mov_b32_e32 v27, v70
	v_mov_b32_e32 v28, v70
	v_mov_b32_e32 v29, v70
	v_mov_b32_e32 v78, v70
	v_mov_b32_e32 v79, v70
	v_mov_b32_e32 v80, v70
	v_mov_b32_e32 v81, v70
	v_mov_b32_e32 v50, v70
	v_mov_b32_e32 v51, v70
	v_mov_b32_e32 v52, v70
	v_mov_b32_e32 v53, v70

;     __device__ __forceinline__ void operator()(f32x4 (&acc)[2][2][4][2], const Unit& u, int wr, int wc, int fr, int fq) const {
;     ...
;         asm volatile("s_waitcnt vmcnt(0) lgkmcnt(0)" ::: "memory"); __builtin_amdgcn_s_barrier(); asm volatile("" ::: "memory");
;         if (tid < 256) { const float* sl = xbuf + (size_t)(u.pm * BM + tid) * 4; float t = 0.f;
; #pragma unroll
;             for (int q = 0; q < 4; ++q) t += __hip_atomic_load(sl + q, __ATOMIC_RELAXED, __HIP_MEMORY_SCOPE_AGENT);
;             S[tid] = rsqrtf(t * (1.0f / DM) + EPS); }
.LBB0_682:
	s_or_b64 exec, exec, s[36:37]
	s_waitcnt vmcnt(0) lgkmcnt(0)
	s_barrier
	s_mov_b64 s[34:35], exec
	v_readlane_b32 s36, v253, 22
	v_readlane_b32 s37, v253, 23
	s_and_b64 s[36:37], s[34:35], s[36:37]
	s_mov_b64 exec, s[36:37]
	s_cbranch_execz .LBB0_684
	v_lshl_add_u64 v[130:131], v[130:131], 4, s[24:25]
	flat_load_dword v132, v[130:131] sc1
	flat_load_dword v133, v[130:131] offset:4 sc1
	flat_load_dword v134, v[130:131] offset:8 sc1
	flat_load_dword v135, v[130:131] offset:12 sc1
	s_mov_b32 s2, 0x800000
	s_waitcnt vmcnt(0) lgkmcnt(0)
	v_add_f32_e32 v132, 0, v132
	v_add_f32_e32 v132, v132, v133
	v_add_f32_e32 v132, v132, v134
	v_add_f32_e32 v130, v132, v135
	v_fmamk_f32 v130, v130, 0x3a800000, v201
	v_cmp_gt_f32_e32 vcc, s2, v130
	v_mul_f32_e32 v131, 0x4b800000, v130
	v_readlane_b32 s2, v250, 22
	v_cndmask_b32_e32 v130, v130, v131, vcc
	v_rsq_f32_e32 v130, v130
	s_nop 0
	v_mul_f32_e32 v131, 0x45800000, v130
	v_cndmask_b32_e32 v130, v130, v131, vcc
	v_lshl_add_u32 v131, v200, 2, s2
	ds_write_b32 v131, v130
